# grid barrier: last XCC leader releases all XGEN lines directly (no TOPGEN hop); XCC-local barriers at seams P4-attn, P6-P7, P7-P8 when groups verified single-XCC; G2 mid-step barrier with split prefet
# speedup vs baseline: 1.0230x; 1.0091x over previous
_Z10fwd_kernel4Args:
	s_load_dwordx8 s[68:75], s[0:1], 0x80
	s_load_dword s96, s[0:1], 0xb8
	s_load_dwordx4 s[92:95], s[0:1], 0xa0
	s_load_dwordx2 s[22:23], s[0:1], 0xb0
	s_add_u32 s6, s0, 0xb0
	v_and_b32_e32 v1, 0x3ff, v0
	s_addc_u32 s7, s1, 0
	v_cmp_gt_u32_e32 vcc, 2, v1
	s_and_saveexec_b64 s[4:5], vcc
	v_lshl_add_u32 v2, v1, 2, 0
	v_add_u32_e32 v2, 0x23fc0, v2
	v_mov_b32_e32 v3, 0
	ds_write_b32 v2, v3
	s_or_b64 exec, exec, s[4:5]
	s_waitcnt lgkmcnt(0)
	s_barrier
	s_mov_b32 s3, 1
	v_writelane_b32 v244, s3, 42
	s_mov_b32 s3, 0
	v_writelane_b32 v244, s3, 43
	v_writelane_b32 v244, s22, 41
	s_getreg_b32 s3, hwreg(HW_REG_XCC_ID, 0, 4)
	s_and_b32 s33, s3, 15
	v_cmp_eq_u32_e32 vcc, 0, v1
	s_and_saveexec_b64 s[4:5], vcc
	s_cbranch_execz .LBB0_5
	s_mov_b64 s[8:9], exec
	v_mbcnt_lo_u32_b32 v2, s8, 0
	v_mbcnt_hi_u32_b32 v2, s9, v2
	v_cmp_eq_u32_e32 vcc, 0, v2
	s_and_b64 s[10:11], exec, vcc
	s_mov_b64 exec, s[10:11]
	s_cbranch_execz .LBB0_5
	s_lshl_b32 s3, s33, 8
	s_bcnt1_i32_b64 s8, s[8:9]
	v_mov_b32_e32 v2, s3
	v_mov_b32_e32 v3, s8
	global_atomic_add v2, v3, s[92:93] offset:1024
.LBB0_5:
	s_or_b64 exec, exec, s[4:5]
	v_cmp_eq_u32_e32 vcc, 0, v1
	s_and_saveexec_b64 s[4:5], vcc
	s_cbranch_execz .Lgrp_skip
	s_and_b32 s3, s2, 7
	s_lshl_b32 s3, s3, 8
	s_add_i32 s3, s3, 0x5000
	v_mov_b32_e32 v2, s3
	s_lshl_b32 s3, 1, s33
	v_mov_b32_e32 v3, s3
	global_atomic_or v2, v3, s[92:93]

.LBB0_203:
	s_cmp_gt_i32 s95, 2
	v_readlane_b32 s34, v245, 7
	s_cselect_b64 s[0:1], -1, 0
	v_readlane_b32 s35, v245, 8
	s_and_b64 s[4:5], s[10:11], s[0:1]
	s_mul_i32 s8, s35, s34
	s_cmp_lt_u32 s14, 64
	s_cselect_b64 s[6:7], -1, 0
	s_mul_i32 s13, s8, s96
	s_add_u32 s8, s92, 0x200
	s_addc_u32 s9, s93, 0
	s_add_u32 s20, s92, 0x1000
	s_addc_u32 s21, s93, 0
	s_add_u32 s22, s92, 0x1100
	s_addc_u32 s23, s93, 0
	s_add_u32 s16, s92, 0x1200
	s_addc_u32 s17, s93, 0
	s_add_u32 s18, s92, 0x1300
	s_addc_u32 s19, s93, 0
	v_writelane_b32 v245, s8, 13
	s_cmp_eq_u32 s33, 15
	v_cndmask_b32_e64 v0, 0, 1, s[6:7]
	v_writelane_b32 v245, s9, 14
	s_cselect_b64 s[8:9], -1, 0
	v_writelane_b32 v245, s8, 15
	s_cmp_eq_u32 s33, 14
	s_nop 0
	v_writelane_b32 v245, s9, 16
	s_cselect_b64 s[8:9], -1, 0
	v_writelane_b32 v245, s8, 17
	s_cmp_eq_u32 s33, 13
	s_nop 0
	v_writelane_b32 v245, s9, 18
	s_cselect_b64 s[8:9], -1, 0
	v_writelane_b32 v245, s8, 19
	s_cmp_eq_u32 s33, 12
	s_nop 0
	v_writelane_b32 v245, s9, 20
	s_cselect_b64 s[8:9], -1, 0
	v_writelane_b32 v245, s8, 21
	s_cmp_eq_u32 s33, 11
	s_nop 0
	v_writelane_b32 v245, s9, 22
	s_cselect_b64 s[8:9], -1, 0
	v_writelane_b32 v245, s8, 23
	s_cmp_eq_u32 s33, 10
	s_nop 0
	v_writelane_b32 v245, s9, 24
	s_cselect_b64 s[8:9], -1, 0
	v_writelane_b32 v245, s8, 25
	s_cmp_eq_u32 s33, 9
	s_nop 0
	v_writelane_b32 v245, s9, 26
	s_cselect_b64 s[8:9], -1, 0
	v_writelane_b32 v245, s8, 27
	s_cmp_eq_u32 s33, 8
	s_nop 0
	v_writelane_b32 v245, s9, 28
	s_cselect_b64 s[8:9], -1, 0
	v_writelane_b32 v245, s8, 29
	s_cmp_eq_u32 s33, 7
	s_nop 0
	v_writelane_b32 v245, s9, 30
	s_cselect_b64 s[8:9], -1, 0
	v_writelane_b32 v245, s8, 31
	s_cmp_eq_u32 s33, 6
	s_nop 0
	v_writelane_b32 v245, s9, 32
	s_cselect_b64 s[8:9], -1, 0
	v_writelane_b32 v245, s8, 33
	s_cmp_eq_u32 s33, 5
	s_nop 0
	v_writelane_b32 v245, s9, 34
	s_cselect_b64 s[8:9], -1, 0
	v_writelane_b32 v245, s8, 35
	s_cmp_eq_u32 s33, 4
	s_nop 0
	v_writelane_b32 v245, s9, 36
	s_cselect_b64 s[8:9], -1, 0
	v_writelane_b32 v245, s8, 37
	s_cmp_eq_u32 s33, 3
	s_nop 0
	v_writelane_b32 v245, s9, 38
	s_cselect_b64 s[8:9], -1, 0
	v_writelane_b32 v245, s8, 39
	s_cmp_eq_u32 s33, 2
	s_nop 0
	v_writelane_b32 v245, s9, 40
	s_cselect_b64 s[8:9], -1, 0
	v_writelane_b32 v245, s8, 41
	s_cmp_eq_u32 s33, 1
	s_nop 0
	v_writelane_b32 v245, s9, 42
	s_cselect_b64 s[8:9], -1, 0
	v_writelane_b32 v245, s8, 43
	s_cmp_eq_u32 s33, 0
	s_nop 0
	v_writelane_b32 v245, s9, 44
	s_cselect_b64 s[8:9], -1, 0
	v_writelane_b32 v245, s8, 45
	s_nop 1
	v_writelane_b32 v245, s9, 46
	s_lshl_b32 s8, s33, 8
	s_add_u32 s8, s92, s8
	s_addc_u32 s9, s93, 0
	s_add_u32 s10, s8, 0x1400
	s_addc_u32 s11, s9, 0
	v_writelane_b32 v245, s10, 47
	s_add_u32 s8, s8, 0x2400
	s_addc_u32 s9, s9, 0
	v_writelane_b32 v245, s11, 48
	v_writelane_b32 v245, s8, 49
	s_nop 1
	v_writelane_b32 v245, s9, 50
	s_add_u32 s8, s92, 0x3400
	s_addc_u32 s9, s93, 0
	v_writelane_b32 v245, s8, 51
	s_nop 1
	v_writelane_b32 v245, s9, 52
	s_add_u32 s8, s92, 0x3500
	s_addc_u32 s9, s93, 0
	v_writelane_b32 v245, s8, 53
	s_andn2_b64 vcc, exec, s[4:5]
	v_cmp_ne_u32_e64 s[4:5], 1, v0
	v_writelane_b32 v245, s9, 54
	s_nop 0
	v_writelane_b32 v245, s4, 55
	s_nop 1
	v_writelane_b32 v245, s5, 56
	v_writelane_b32 v245, s13, 57
	v_writelane_b32 v245, s16, 58
	s_nop 1
	v_writelane_b32 v245, s17, 59
	v_writelane_b32 v245, s18, 60
	s_nop 1
	v_writelane_b32 v245, s19, 61
	s_cbranch_vccnz .LBB0_259
	s_waitcnt vmcnt(0)
	v_readlane_b32 s4, v245, 55
	v_readlane_b32 s5, v245, 56
	s_and_b64 vcc, exec, s[4:5]
	s_waitcnt vmcnt(0)
	s_barrier
	s_cbranch_vccnz .LBB0_258
	v_mbcnt_hi_u32_b32 v0, -1, v192
	v_cmp_eq_u32_e32 vcc, 0, v0
	s_and_saveexec_b64 s[4:5], vcc
	s_cbranch_execz .LBB0_257
	s_waitcnt vmcnt(0) lgkmcnt(0)
	v_mov_b32_e32 v1, 1
	v_mov_b32_e32 v0, 0x23fc0
	ds_read_b32 v2, v0
	ds_read_b32 v3, v0 offset:4
	s_getreg_b32 s12, hwreg(HW_REG_XCC_ID, 0, 4)
	s_and_b32 s12, s12, 15
	s_lshl_b32 s12, s12, 8
	s_add_i32 s10, s12, 0x1400
	s_add_i32 s12, s12, 0x2400
	v_mov_b32_e32 v5, s10
	v_mov_b32_e32 v6, s12
	global_atomic_add v7, v5, v1, s[92:93] sc0
	v_readlane_b32 s6, v244, 42
	s_add_i32 s6, s6, 1
	s_nop 0
	v_writelane_b32 v244, s6, 42
	s_waitcnt lgkmcnt(0)
	v_readfirstlane_b32 s10, v2
	v_readfirstlane_b32 s11, v3
	s_mul_i32 s10, s10, s6
	s_mul_i32 s11, s11, s6
	s_waitcnt vmcnt(0)
	v_readfirstlane_b32 s12, v7
	s_add_i32 s12, s12, 1
	s_cmp_eq_u32 s12, s10
	s_cbranch_scc0 .Lxb1_wait
	buffer_wbl2 sc1
	s_waitcnt vmcnt(0)
	v_mov_b32_e32 v8, 0x3400
	global_atomic_add v7, v8, v1, s[92:93] sc0
	s_waitcnt vmcnt(0)
	v_readfirstlane_b32 s12, v7
	s_add_i32 s12, s12, 1
	s_cmp_eq_u32 s12, s11
	s_cbranch_scc0 .Lxb1_wait
	v_mov_b32_e32 v8, 0x2400
	global_atomic_add v8, v1, s[92:93]
	global_atomic_add v8, v1, s[92:93] offset:256
	global_atomic_add v8, v1, s[92:93] offset:512
	global_atomic_add v8, v1, s[92:93] offset:768
	global_atomic_add v8, v1, s[92:93] offset:1024
	global_atomic_add v8, v1, s[92:93] offset:1280
	global_atomic_add v8, v1, s[92:93] offset:1536
	global_atomic_add v8, v1, s[92:93] offset:1792
	global_atomic_add v8, v1, s[92:93] offset:2048
	global_atomic_add v8, v1, s[92:93] offset:2304
	global_atomic_add v8, v1, s[92:93] offset:2560
	global_atomic_add v8, v1, s[92:93] offset:2816
	global_atomic_add v8, v1, s[92:93] offset:3072
	global_atomic_add v8, v1, s[92:93] offset:3328
	global_atomic_add v8, v1, s[92:93] offset:3584
	global_atomic_add v8, v1, s[92:93] offset:3840
	s_branch .Lxb1_done
.Lxb1_wait:
	s_mov_b32 s11, 0
.Lxb1_poll:
	global_load_dword v7, v6, s[92:93] sc1
	s_waitcnt vmcnt(0)
	v_readfirstlane_b32 s12, v7
	s_cmp_ge_u32 s12, s6
	s_cbranch_scc1 .Lxb1_done
	s_add_i32 s11, s11, 1
	s_cmp_lt_u32 s11, 0x40000
	s_cbranch_scc0 .Lxb1_done
	s_sleep 1
	s_branch .Lxb1_poll
.Lxb1_done:
	buffer_inv sc1
	s_waitcnt vmcnt(0)
	v_mov_b32_e32 v8, 0x5000
	global_load_dword v9, v8, s[92:93] sc1
	global_load_dword v10, v8, s[92:93] offset:256 sc1
	global_load_dword v11, v8, s[92:93] offset:512 sc1
	global_load_dword v12, v8, s[92:93] offset:768 sc1
	global_load_dword v13, v8, s[92:93] offset:1024 sc1
	global_load_dword v14, v8, s[92:93] offset:1280 sc1
	global_load_dword v15, v8, s[92:93] offset:1536 sc1
	global_load_dword v16, v8, s[92:93] offset:1792 sc1
	s_waitcnt vmcnt(0)
	v_mov_b32_e32 v2, 0
	v_add_u32_e32 v3, -1, v9
	v_and_b32_e32 v3, v3, v9
	v_or_b32_e32 v2, v2, v3
	v_add_u32_e32 v3, -1, v10
	v_and_b32_e32 v3, v3, v10
	v_or_b32_e32 v2, v2, v3
	v_add_u32_e32 v3, -1, v11
	v_and_b32_e32 v3, v3, v11
	v_or_b32_e32 v2, v2, v3
	v_add_u32_e32 v3, -1, v12
	v_and_b32_e32 v3, v3, v12
	v_or_b32_e32 v2, v2, v3
	v_add_u32_e32 v3, -1, v13
	v_and_b32_e32 v3, v3, v13
	v_or_b32_e32 v2, v2, v3
	v_add_u32_e32 v3, -1, v14
	v_and_b32_e32 v3, v3, v14
	v_or_b32_e32 v2, v2, v3
	v_add_u32_e32 v3, -1, v15
	v_and_b32_e32 v3, v3, v15
	v_or_b32_e32 v2, v2, v3
	v_add_u32_e32 v3, -1, v16
	v_and_b32_e32 v3, v3, v16
	v_or_b32_e32 v2, v2, v3
	s_nop 0
	v_readfirstlane_b32 s12, v2
	v_readlane_b32 s11, v244, 41
	s_cmp_eq_u32 s12, 0
	s_cselect_b32 s12, 1, 0
	s_cmp_eq_u32 s11, 0x100
	s_cselect_b32 s12, s12, 0
	s_nop 0
	v_writelane_b32 v244, s12, 43

.LBB0_495:
	s_cmp_gt_i32 s95, 3
	s_cselect_b64 s[4:5], -1, 0
	s_and_b64 s[0:1], s[36:37], s[4:5]
	s_andn2_b64 vcc, exec, s[0:1]
	s_cbranch_vccnz .LBB0_551
	s_waitcnt vmcnt(0)
	v_readlane_b32 s0, v245, 55
	v_readlane_b32 s1, v245, 56
	s_and_b64 vcc, exec, s[0:1]
	s_waitcnt vmcnt(0)
	s_barrier
	s_cbranch_vccnz .LBB0_550
	v_mbcnt_hi_u32_b32 v0, -1, v192
	v_cmp_eq_u32_e32 vcc, 0, v0
	s_and_saveexec_b64 s[0:1], vcc
	v_readlane_b32 s13, v245, 57
	s_cbranch_execz .LBB0_549
	s_waitcnt vmcnt(0) lgkmcnt(0)
	v_mov_b32_e32 v1, 1
	v_mov_b32_e32 v0, 0x23fc0
	ds_read_b32 v2, v0
	ds_read_b32 v3, v0 offset:4
	s_getreg_b32 s12, hwreg(HW_REG_XCC_ID, 0, 4)
	s_and_b32 s12, s12, 15
	s_lshl_b32 s12, s12, 8
	s_add_i32 s10, s12, 0x1400
	s_add_i32 s12, s12, 0x2400
	v_mov_b32_e32 v5, s10
	v_mov_b32_e32 v6, s12
	global_atomic_add v7, v5, v1, s[92:93] sc0
	v_readlane_b32 s6, v244, 42
	s_add_i32 s6, s6, 1
	s_nop 0
	v_writelane_b32 v244, s6, 42
	s_waitcnt lgkmcnt(0)
	v_readfirstlane_b32 s10, v2
	v_readfirstlane_b32 s11, v3
	s_mul_i32 s10, s10, s6
	s_mul_i32 s11, s11, s6
	s_waitcnt vmcnt(0)
	v_readfirstlane_b32 s12, v7
	s_add_i32 s12, s12, 1
	s_cmp_eq_u32 s12, s10
	s_cbranch_scc0 .Lxb2_wait
	buffer_wbl2 sc1
	s_waitcnt vmcnt(0)
	v_mov_b32_e32 v8, 0x3400
	global_atomic_add v7, v8, v1, s[92:93] sc0
	s_waitcnt vmcnt(0)
	v_readfirstlane_b32 s12, v7
	s_add_i32 s12, s12, 1
	s_cmp_eq_u32 s12, s11
	s_cbranch_scc0 .Lxb2_wait
	v_mov_b32_e32 v8, 0x2400
	global_atomic_add v8, v1, s[92:93]
	global_atomic_add v8, v1, s[92:93] offset:256
	global_atomic_add v8, v1, s[92:93] offset:512
	global_atomic_add v8, v1, s[92:93] offset:768
	global_atomic_add v8, v1, s[92:93] offset:1024
	global_atomic_add v8, v1, s[92:93] offset:1280
	global_atomic_add v8, v1, s[92:93] offset:1536
	global_atomic_add v8, v1, s[92:93] offset:1792
	global_atomic_add v8, v1, s[92:93] offset:2048
	global_atomic_add v8, v1, s[92:93] offset:2304
	global_atomic_add v8, v1, s[92:93] offset:2560
	global_atomic_add v8, v1, s[92:93] offset:2816
	global_atomic_add v8, v1, s[92:93] offset:3072
	global_atomic_add v8, v1, s[92:93] offset:3328
	global_atomic_add v8, v1, s[92:93] offset:3584
	global_atomic_add v8, v1, s[92:93] offset:3840
	s_branch .Lxb2_done

.Lxb2_done:
	buffer_inv sc1
	s_waitcnt vmcnt(0)

.Lg2c_noload:
	s_waitcnt lgkmcnt(8)
	v_mfma_f32_16x16x32_bf16 v[176:179], v[144:147], v[70:73], v[176:179]
	v_mfma_f32_16x16x32_bf16 v[196:199], v[160:163], v[70:73], v[196:199]
	v_mfma_f32_16x16x32_bf16 v[180:183], v[148:151], v[70:73], v[180:183]
	v_mfma_f32_16x16x32_bf16 v[200:203], v[164:167], v[70:73], v[200:203]
	v_mfma_f32_16x16x32_bf16 v[184:187], v[152:155], v[70:73], v[184:187]
	v_mfma_f32_16x16x32_bf16 v[204:207], v[168:171], v[70:73], v[204:207]
	v_mfma_f32_16x16x32_bf16 v[188:191], v[156:159], v[70:73], v[188:191]
	v_mfma_f32_16x16x32_bf16 v[208:211], v[172:175], v[70:73], v[208:211]
	s_waitcnt lgkmcnt(0)
	s_barrier
	ds_read_b128 v[112:115], v238 offset:32768
	ds_read_b128 v[116:119], v238 offset:34816
	ds_read_b128 v[120:123], v238 offset:36864
	ds_read_b128 v[124:127], v238 offset:38912
	ds_read_b128 v[128:131], v238 offset:40960
	ds_read_b128 v[132:135], v238 offset:43008
	ds_read_b128 v[136:139], v238 offset:45056
	ds_read_b128 v[140:143], v238 offset:47104
	v_mfma_f32_16x16x32_bf16 v[176:179], v[80:83], v[74:77], v[176:179]
	v_mfma_f32_16x16x32_bf16 v[180:183], v[84:87], v[74:77], v[180:183]
	v_mfma_f32_16x16x32_bf16 v[184:187], v[88:91], v[74:77], v[184:187]
	v_mfma_f32_16x16x32_bf16 v[188:191], v[92:95], v[74:77], v[188:191]
	v_mfma_f32_16x16x32_bf16 v[196:199], v[96:99], v[74:77], v[196:199]
	v_sub_f32_e32 v212, v212, v176
	v_sub_f32_e32 v213, v213, v177
	v_sub_f32_e32 v214, v214, v178
	v_sub_f32_e32 v215, v215, v179
	v_mfma_f32_16x16x32_bf16 v[200:203], v[100:103], v[74:77], v[200:203]
	v_sub_f32_e32 v216, v216, v180
	v_sub_f32_e32 v217, v217, v181
	v_sub_f32_e32 v218, v218, v182
	v_sub_f32_e32 v219, v219, v183
	v_mfma_f32_16x16x32_bf16 v[204:207], v[104:107], v[74:77], v[204:207]
	v_sub_f32_e32 v220, v220, v184
	v_sub_f32_e32 v221, v221, v185
	v_sub_f32_e32 v222, v222, v186
	v_sub_f32_e32 v223, v223, v187
	v_mfma_f32_16x16x32_bf16 v[208:211], v[108:111], v[74:77], v[208:211]
	v_sub_f32_e32 v224, v224, v188
	v_sub_f32_e32 v225, v225, v189
	v_sub_f32_e32 v226, v226, v190
	v_sub_f32_e32 v227, v227, v191
	ds_read_b128 v[144:147], v238 offset:33792
	ds_read_b128 v[148:151], v238 offset:35840
	ds_read_b128 v[152:155], v238 offset:37888
	ds_read_b128 v[156:159], v238 offset:39936
	ds_read_b128 v[160:163], v238 offset:41984
	ds_read_b128 v[164:167], v238 offset:44032
	ds_read_b128 v[168:171], v238 offset:46080
	ds_read_b128 v[172:175], v238 offset:48128
	v_cvt_pk_bf16_f32 v228, v212, v213
	v_cvt_pk_bf16_f32 v229, v214, v215
	v_cvt_pk_bf16_f32 v230, v216, v217
	v_cvt_pk_bf16_f32 v231, v218, v219
	v_cvt_pk_bf16_f32 v232, v220, v221
	v_cvt_pk_bf16_f32 v233, v222, v223
	v_cvt_pk_bf16_f32 v234, v224, v225
	v_cvt_pk_bf16_f32 v235, v226, v227
	s_waitcnt lgkmcnt(8)
	s_nop 1
	v_mfma_f32_16x16x32_bf16 v[4:7], v[112:115], v[228:231], v[4:7]
	v_mfma_f32_16x16x32_bf16 v[8:11], v[116:119], v[228:231], v[8:11]
	v_mfma_f32_16x16x32_bf16 v[12:15], v[120:123], v[228:231], v[12:15]
	v_mfma_f32_16x16x32_bf16 v[16:19], v[124:127], v[228:231], v[16:19]
	v_mfma_f32_16x16x32_bf16 v[20:23], v[128:131], v[228:231], v[20:23]
	v_mfma_f32_16x16x32_bf16 v[24:27], v[132:135], v[228:231], v[24:27]
	v_mfma_f32_16x16x32_bf16 v[28:31], v[136:139], v[228:231], v[28:31]
	v_mfma_f32_16x16x32_bf16 v[32:35], v[140:143], v[228:231], v[32:35]
	ds_read_b128 v[80:83], v238 offset:49152
	ds_read_b128 v[84:87], v238 offset:51200
	ds_read_b128 v[88:91], v238 offset:53248
	ds_read_b128 v[92:95], v238 offset:55296
	ds_read_b128 v[96:99], v238 offset:50176
	ds_read_b128 v[100:103], v238 offset:52224
	ds_read_b128 v[104:107], v238 offset:54272
	ds_read_b128 v[108:111], v238 offset:56320
	s_waitcnt lgkmcnt(8)
	v_mfma_f32_16x16x32_bf16 v[4:7], v[144:147], v[232:235], v[4:7]
	v_mfma_f32_16x16x32_bf16 v[8:11], v[148:151], v[232:235], v[8:11]
	v_mfma_f32_16x16x32_bf16 v[12:15], v[152:155], v[232:235], v[12:15]
	v_mfma_f32_16x16x32_bf16 v[16:19], v[156:159], v[232:235], v[16:19]
	v_mfma_f32_16x16x32_bf16 v[20:23], v[160:163], v[232:235], v[20:23]
	v_mfma_f32_16x16x32_bf16 v[24:27], v[164:167], v[232:235], v[24:27]
	v_mfma_f32_16x16x32_bf16 v[28:31], v[168:171], v[232:235], v[28:31]
	v_mfma_f32_16x16x32_bf16 v[32:35], v[172:175], v[232:235], v[32:35]
	s_waitcnt lgkmcnt(0)
	v_mfma_f32_16x16x32_bf16 v[196:199], v[80:83], v[228:231], v[196:199]
	v_mfma_f32_16x16x32_bf16 v[200:203], v[84:87], v[228:231], v[200:203]
	v_mfma_f32_16x16x32_bf16 v[204:207], v[88:91], v[228:231], v[204:207]
	v_mfma_f32_16x16x32_bf16 v[208:211], v[92:95], v[228:231], v[208:211]
	v_mfma_f32_16x16x32_bf16 v[196:199], v[96:99], v[232:235], v[196:199]
	v_mfma_f32_16x16x32_bf16 v[200:203], v[100:103], v[232:235], v[200:203]
	v_mfma_f32_16x16x32_bf16 v[204:207], v[104:107], v[232:235], v[204:207]
	v_mfma_f32_16x16x32_bf16 v[208:211], v[108:111], v[232:235], v[208:211]
	s_nop 7
	s_nop 3
	v_cvt_pk_bf16_f32 v112, v196, v197
	v_cvt_pk_bf16_f32 v113, v198, v199
	v_cvt_pk_bf16_f32 v114, v200, v201
	v_cvt_pk_bf16_f32 v115, v202, v203
	v_cvt_pk_bf16_f32 v116, v204, v205
	v_cvt_pk_bf16_f32 v117, v206, v207
	v_cvt_pk_bf16_f32 v118, v208, v209
	v_cvt_pk_bf16_f32 v119, v210, v211
	global_store_short v239, v112, s[28:29]
	global_store_short_d16_hi v239, v112, s[28:29] offset:2048
	global_store_short v240, v113, s[28:29]
	global_store_short_d16_hi v240, v113, s[28:29] offset:2048
	global_store_short v241, v114, s[28:29]
	global_store_short_d16_hi v241, v114, s[28:29] offset:2048
	global_store_short v242, v115, s[28:29]
	global_store_short_d16_hi v242, v115, s[28:29] offset:2048
	global_store_short v243, v116, s[28:29]
	global_store_short_d16_hi v243, v116, s[28:29] offset:2048
	global_store_short v246, v117, s[28:29]
	global_store_short_d16_hi v246, v117, s[28:29] offset:2048
	global_store_short v247, v118, s[28:29]
	global_store_short_d16_hi v247, v118, s[28:29] offset:2048
	global_store_short v248, v119, s[28:29]
	global_store_short_d16_hi v248, v119, s[28:29] offset:2048
	s_add_u32 s28, s28, 0x20000
	s_addc_u32 s29, s29, 0
	s_add_u32 s48, s48, 0x20000
	s_addc_u32 s49, s49, 0
	s_add_u32 s36, s36, 32
	s_addc_u32 s37, s37, 0
	v_xor_b32_e32 v238, 0xe000, v238
	s_add_i32 s19, s19, 1
	s_cmp_lt_u32 s19, 32
	s_barrier
	s_cbranch_scc1 .Lg2c_loop
	s_branch .Lg2_exit
.Lg2h_setup:
	s_lshr_b32 s83, s21, 10
	s_sub_u32 s83, s83, 2
	s_lshl_b32 s79, s83, 13
	s_lshl_b32 s82, s83, 10
	v_add_u32_e32 v70, s82, v252
	v_add_u32_e32 v71, 0x1800, v70
	s_add_u32 s82, s82, 0xc000
	s_mov_b32 s78, 0xe000
	s_add_u32 s46, s92, s46
	s_addc_u32 s47, s93, s47
	s_add_u32 s46, s46, 0x6d20000
	s_addc_u32 s47, s47, 0
	s_lshr_b32 s4, s83, 1
	s_lshl_b32 s4, s4, 25
	s_add_u32 s46, s46, s4
	s_addc_u32 s47, s47, 0
	s_and_b32 s4, s83, 1
	s_lshl_b32 s4, s4, 13
	s_add_u32 s46, s46, s4
	s_addc_u32 s47, s47, 0
	s_add_u32 s42, s92, s42
	s_addc_u32 s43, s93, s43
	s_add_u32 s42, s42, 0xcd10000
	s_addc_u32 s43, s43, 0
	v_mov_b32_e32 v62, v252
	v_add_u32_e32 v63, 0x400, v252
	v_add_u32_e32 v64, 0x800, v252
	v_add_u32_e32 v65, 0xc00, v252
	v_add_u32_e32 v66, 0x1000, v252
	v_add_u32_e32 v67, 0x1400, v252
	v_add_u32_e32 v68, 0x1800, v252
	v_add_u32_e32 v69, 0x1c00, v252
	s_mov_b32 s19, 0
	s_mov_b32 s18, 0
	s_cmp_lt_u32 s83, 4
	s_cbranch_scc0 .Lg2h_loop
	s_add_i32 s4, s79, s78
	s_mov_b32 m0, s4
	s_nop 0
	global_load_lds_dwordx4 v62, s[46:47]
	s_add_i32 m0, s4, 0x400
	s_nop 0
	global_load_lds_dwordx4 v63, s[46:47]
	s_add_i32 m0, s4, 0x800
	s_nop 0
	global_load_lds_dwordx4 v64, s[46:47]
	s_add_i32 m0, s4, 0xc00
	s_nop 0
	global_load_lds_dwordx4 v65, s[46:47]
	s_add_i32 m0, s4, 0x1000
	s_nop 0
	global_load_lds_dwordx4 v66, s[46:47]
	s_add_i32 m0, s4, 0x1400
	s_nop 0
	global_load_lds_dwordx4 v67, s[46:47]
	s_add_i32 m0, s4, 0x1800
	s_nop 0
	global_load_lds_dwordx4 v68, s[46:47]
	s_add_i32 m0, s4, 0x1c00
	s_nop 0
	global_load_lds_dwordx4 v69, s[46:47]
	s_add_u32 s46, s46, 0x20000
	s_addc_u32 s47, s47, 0
.Lg2h_loop:
	s_cmp_lt_u32 s19, 31
	s_cbranch_scc0 .Lg2h_noka
	s_cmp_lt_u32 s83, 4
	s_cbranch_scc1 .Lg2h_nok
	s_add_i32 s4, s79, s78
	s_mov_b32 m0, s4
	s_nop 0
	global_load_lds_dwordx4 v62, s[46:47]
	s_add_i32 m0, s4, 0x400
	s_nop 0
	global_load_lds_dwordx4 v63, s[46:47]
	s_add_i32 m0, s4, 0x800
	s_nop 0
	global_load_lds_dwordx4 v64, s[46:47]
	s_add_i32 m0, s4, 0xc00
	s_nop 0
	global_load_lds_dwordx4 v65, s[46:47]
	s_add_i32 m0, s4, 0x1000
	s_nop 0
	global_load_lds_dwordx4 v66, s[46:47]
	s_add_i32 m0, s4, 0x1400
	s_nop 0
	global_load_lds_dwordx4 v67, s[46:47]
	s_add_i32 m0, s4, 0x1800
	s_nop 0
	global_load_lds_dwordx4 v68, s[46:47]
	s_add_i32 m0, s4, 0x1c00
	s_nop 0
	global_load_lds_dwordx4 v69, s[46:47]
	s_add_u32 s46, s46, 0x20000
	s_addc_u32 s47, s47, 0
.Lg2h_nok:
	s_add_i32 s4, s82, s78
	s_mov_b32 m0, s4
	s_nop 0
	global_load_lds_dwordx4 v70, s[42:43]
	s_cmp_lt_u32 s83, 2
	s_cbranch_scc0 .Lg2h_no2
	s_add_i32 m0, s4, 0x1800
	s_nop 0
	global_load_lds_dwordx4 v71, s[42:43]
.Lg2h_no2:
	s_add_u32 s42, s42, 0x10000
	s_addc_u32 s43, s43, 0
	s_sub_u32 s78, 0xe000, s78
.Lg2h_noka:
	s_cmp_lt_u32 s19, 30
	s_cbranch_scc0 .Lg2h_w0a
	s_cmp_lt_u32 s83, 2
	s_cbranch_scc0 .Lg2h_w9a
	s_waitcnt vmcnt(10)
	s_branch .Lg2h_wda
.Lg2h_w9a:
	s_waitcnt vmcnt(9)
	s_branch .Lg2h_wda

.Lg2h_wda:
	s_barrier
	s_cmp_lt_u32 s19, 30
	s_cbranch_scc0 .Lg2h_nowq
	s_cmp_lt_u32 s83, 4
	s_cbranch_scc0 .Lg2h_nowq
	s_add_i32 s4, s79, s18
	s_mov_b32 m0, s4
	s_nop 0
	global_load_lds_dwordx4 v62, s[46:47]
	s_add_i32 m0, s4, 0x400
	s_nop 0
	global_load_lds_dwordx4 v63, s[46:47]
	s_add_i32 m0, s4, 0x800
	s_nop 0
	global_load_lds_dwordx4 v64, s[46:47]
	s_add_i32 m0, s4, 0xc00
	s_nop 0
	global_load_lds_dwordx4 v65, s[46:47]
	s_add_i32 m0, s4, 0x1000
	s_nop 0
	global_load_lds_dwordx4 v66, s[46:47]
	s_add_i32 m0, s4, 0x1400
	s_nop 0
	global_load_lds_dwordx4 v67, s[46:47]
	s_add_i32 m0, s4, 0x1800
	s_nop 0
	global_load_lds_dwordx4 v68, s[46:47]
	s_add_i32 m0, s4, 0x1c00
	s_nop 0
	global_load_lds_dwordx4 v69, s[46:47]
	s_add_u32 s46, s46, 0x20000
	s_addc_u32 s47, s47, 0
	s_sub_u32 s18, 0xe000, s18

.Lg2h_wdb:
	s_add_i32 s19, s19, 1
	s_cmp_lt_u32 s19, 32
	s_barrier
	s_cbranch_scc1 .Lg2h_loop

.LBB0_574:
	s_cmp_gt_i32 s95, 4
	s_cselect_b64 s[4:5], -1, 0
	s_and_b64 s[0:1], s[0:1], s[4:5]
	s_andn2_b64 vcc, exec, s[0:1]
	v_readlane_b32 s14, v245, 57
	s_cbranch_vccnz .LBB0_630
	s_waitcnt vmcnt(0)
	v_readlane_b32 s0, v245, 55
	v_readlane_b32 s1, v245, 56
	s_and_b64 vcc, exec, s[0:1]
	s_waitcnt vmcnt(0)
	s_barrier
	s_cbranch_vccnz .LBB0_629
	v_mbcnt_hi_u32_b32 v0, -1, v192
	v_cmp_eq_u32_e32 vcc, 0, v0
	s_and_saveexec_b64 s[0:1], vcc
	s_cbranch_execz .LBB0_628
	s_waitcnt vmcnt(0) lgkmcnt(0)
	v_mov_b32_e32 v1, 1
	v_mov_b32_e32 v0, 0x23fc0
	ds_read_b32 v2, v0
	ds_read_b32 v3, v0 offset:4
	s_getreg_b32 s12, hwreg(HW_REG_XCC_ID, 0, 4)
	s_and_b32 s12, s12, 15
	s_lshl_b32 s12, s12, 8
	s_add_i32 s10, s12, 0x1400
	s_add_i32 s12, s12, 0x2400
	v_mov_b32_e32 v5, s10
	v_mov_b32_e32 v6, s12
	global_atomic_add v7, v5, v1, s[92:93] sc0
	v_readlane_b32 s6, v244, 42
	s_add_i32 s6, s6, 1
	s_nop 0
	v_writelane_b32 v244, s6, 42
	s_waitcnt lgkmcnt(0)
	v_readfirstlane_b32 s10, v2
	v_readfirstlane_b32 s11, v3
	s_mul_i32 s10, s10, s6
	s_mul_i32 s11, s11, s6
	s_waitcnt vmcnt(0)
	v_readfirstlane_b32 s12, v7
	s_add_i32 s12, s12, 1
	s_cmp_eq_u32 s12, s10
	s_cbranch_scc0 .Lxb3_wait
	buffer_wbl2 sc1
	s_waitcnt vmcnt(0)
	v_mov_b32_e32 v8, 0x3400
	global_atomic_add v7, v8, v1, s[92:93] sc0
	s_waitcnt vmcnt(0)
	v_readfirstlane_b32 s12, v7
	s_add_i32 s12, s12, 1
	s_cmp_eq_u32 s12, s11
	s_cbranch_scc0 .Lxb3_wait
	v_mov_b32_e32 v8, 0x2400
	global_atomic_add v8, v1, s[92:93]
	global_atomic_add v8, v1, s[92:93] offset:256
	global_atomic_add v8, v1, s[92:93] offset:512
	global_atomic_add v8, v1, s[92:93] offset:768
	global_atomic_add v8, v1, s[92:93] offset:1024
	global_atomic_add v8, v1, s[92:93] offset:1280
	global_atomic_add v8, v1, s[92:93] offset:1536
	global_atomic_add v8, v1, s[92:93] offset:1792
	global_atomic_add v8, v1, s[92:93] offset:2048
	global_atomic_add v8, v1, s[92:93] offset:2304
	global_atomic_add v8, v1, s[92:93] offset:2560
	global_atomic_add v8, v1, s[92:93] offset:2816
	global_atomic_add v8, v1, s[92:93] offset:3072
	global_atomic_add v8, v1, s[92:93] offset:3328
	global_atomic_add v8, v1, s[92:93] offset:3584
	global_atomic_add v8, v1, s[92:93] offset:3840
	s_branch .Lxb3_done

.LBB0_684:
	s_cmp_gt_i32 s95, 5
	s_cselect_b64 s[0:1], -1, 0
	s_and_b64 s[4:5], s[40:41], s[0:1]
	v_readlane_b32 s64, v245, 53
	s_andn2_b64 vcc, exec, s[4:5]
	v_readlane_b32 s65, v245, 54
	s_cbranch_vccnz .LBB0_740
	s_waitcnt vmcnt(0)
	v_readlane_b32 s4, v245, 55
	v_readlane_b32 s5, v245, 56
	s_and_b64 vcc, exec, s[4:5]
	s_waitcnt vmcnt(0)
	s_barrier
	s_cbranch_vccnz .LBB0_739
	v_mbcnt_hi_u32_b32 v0, -1, v192
	v_cmp_eq_u32_e32 vcc, 0, v0
	s_and_saveexec_b64 s[4:5], vcc
	s_cbranch_execz .LBB0_738
	s_waitcnt vmcnt(0) lgkmcnt(0)
	v_mov_b32_e32 v1, 1
	v_readlane_b32 s11, v244, 43
	s_cmp_eq_u32 s11, 1
	s_cbranch_scc0 .Lxb4_glob
	s_and_b32 s12, s2, 7
	s_lshl_b32 s10, s12, 8
	s_add_i32 s10, s10, 0x6000
	v_mov_b32_e32 v6, s10
	global_atomic_add v6, v1, s[92:93]
	v_readlane_b32 s11, v244, 41
	s_sub_i32 s11, s11, s12
	s_add_i32 s11, s11, 7
	s_lshr_b32 s11, s11, 3
	s_mul_i32 s6, s11, 1
	s_branch .Lxb4_wait
.Lxb4_glob:
	v_mov_b32_e32 v0, 0x23fc0
	ds_read_b32 v2, v0
	ds_read_b32 v3, v0 offset:4
	s_getreg_b32 s12, hwreg(HW_REG_XCC_ID, 0, 4)
	s_and_b32 s12, s12, 15
	s_lshl_b32 s12, s12, 8
	s_add_i32 s10, s12, 0x1400
	s_add_i32 s12, s12, 0x2400
	v_mov_b32_e32 v5, s10
	v_mov_b32_e32 v6, s12
	global_atomic_add v7, v5, v1, s[92:93] sc0
	v_readlane_b32 s6, v244, 42
	s_add_i32 s6, s6, 1
	s_nop 0
	v_writelane_b32 v244, s6, 42
	s_waitcnt lgkmcnt(0)
	v_readfirstlane_b32 s10, v2
	v_readfirstlane_b32 s11, v3
	s_mul_i32 s10, s10, s6
	s_mul_i32 s11, s11, s6
	s_waitcnt vmcnt(0)
	v_readfirstlane_b32 s12, v7
	s_add_i32 s12, s12, 1
	s_cmp_eq_u32 s12, s10
	s_cbranch_scc0 .Lxb4_wait
	buffer_wbl2 sc1
	s_waitcnt vmcnt(0)
	v_mov_b32_e32 v8, 0x3400
	global_atomic_add v7, v8, v1, s[92:93] sc0
	s_waitcnt vmcnt(0)
	v_readfirstlane_b32 s12, v7
	s_add_i32 s12, s12, 1
	s_cmp_eq_u32 s12, s11
	s_cbranch_scc0 .Lxb4_wait
	v_mov_b32_e32 v8, 0x2400
	global_atomic_add v8, v1, s[92:93]
	global_atomic_add v8, v1, s[92:93] offset:256
	global_atomic_add v8, v1, s[92:93] offset:512
	global_atomic_add v8, v1, s[92:93] offset:768
	global_atomic_add v8, v1, s[92:93] offset:1024
	global_atomic_add v8, v1, s[92:93] offset:1280
	global_atomic_add v8, v1, s[92:93] offset:1536
	global_atomic_add v8, v1, s[92:93] offset:1792
	global_atomic_add v8, v1, s[92:93] offset:2048
	global_atomic_add v8, v1, s[92:93] offset:2304
	global_atomic_add v8, v1, s[92:93] offset:2560
	global_atomic_add v8, v1, s[92:93] offset:2816
	global_atomic_add v8, v1, s[92:93] offset:3072
	global_atomic_add v8, v1, s[92:93] offset:3328
	global_atomic_add v8, v1, s[92:93] offset:3584
	global_atomic_add v8, v1, s[92:93] offset:3840
	s_branch .Lxb4_done

.LBB0_813:
	s_cmp_gt_i32 s95, 6
	v_readlane_b32 s0, v244, 13
	s_cselect_b64 s[4:5], -1, 0
	v_readlane_b32 s1, v244, 14
	s_and_b64 s[0:1], s[0:1], s[4:5]
	v_readlane_b32 s58, v245, 3
	v_readlane_b32 s24, v245, 58
	v_readlane_b32 s30, v245, 60
	v_readlane_b32 s60, v245, 5
	s_andn2_b64 vcc, exec, s[0:1]
	v_readlane_b32 s59, v245, 4
	v_readlane_b32 s25, v245, 59
	v_readlane_b32 s31, v245, 61
	v_readlane_b32 s61, v245, 6
	s_cbranch_vccnz .LBB0_869
	s_waitcnt vmcnt(0)
	v_readlane_b32 s0, v245, 55
	v_readlane_b32 s1, v245, 56
	s_and_b64 vcc, exec, s[0:1]
	s_waitcnt vmcnt(0)
	s_barrier
	s_cbranch_vccnz .LBB0_868
	v_mbcnt_hi_u32_b32 v0, -1, v192
	v_cmp_eq_u32_e32 vcc, 0, v0
	s_and_saveexec_b64 s[0:1], vcc
	s_cbranch_execz .LBB0_867
	s_waitcnt vmcnt(0) lgkmcnt(0)
	v_mov_b32_e32 v1, 1
	v_mov_b32_e32 v0, 0x23fc0
	ds_read_b32 v2, v0
	ds_read_b32 v3, v0 offset:4
	s_getreg_b32 s12, hwreg(HW_REG_XCC_ID, 0, 4)
	s_and_b32 s12, s12, 15
	s_lshl_b32 s12, s12, 8
	s_add_i32 s10, s12, 0x1400
	s_add_i32 s12, s12, 0x2400
	v_mov_b32_e32 v5, s10
	v_mov_b32_e32 v6, s12
	global_atomic_add v7, v5, v1, s[92:93] sc0
	v_readlane_b32 s6, v244, 42
	s_add_i32 s6, s6, 1
	s_nop 0
	v_writelane_b32 v244, s6, 42
	s_waitcnt lgkmcnt(0)
	v_readfirstlane_b32 s10, v2
	v_readfirstlane_b32 s11, v3
	s_mul_i32 s10, s10, s6
	s_mul_i32 s11, s11, s6
	s_waitcnt vmcnt(0)
	v_readfirstlane_b32 s12, v7
	s_add_i32 s12, s12, 1
	s_cmp_eq_u32 s12, s10
	s_cbranch_scc0 .Lxb5_wait
	buffer_wbl2 sc1
	s_waitcnt vmcnt(0)
	v_mov_b32_e32 v8, 0x3400
	global_atomic_add v7, v8, v1, s[92:93] sc0
	s_waitcnt vmcnt(0)
	v_readfirstlane_b32 s12, v7
	s_add_i32 s12, s12, 1
	s_cmp_eq_u32 s12, s11
	s_cbranch_scc0 .Lxb5_wait
	v_mov_b32_e32 v8, 0x2400
	global_atomic_add v8, v1, s[92:93]
	global_atomic_add v8, v1, s[92:93] offset:256
	global_atomic_add v8, v1, s[92:93] offset:512
	global_atomic_add v8, v1, s[92:93] offset:768
	global_atomic_add v8, v1, s[92:93] offset:1024
	global_atomic_add v8, v1, s[92:93] offset:1280
	global_atomic_add v8, v1, s[92:93] offset:1536
	global_atomic_add v8, v1, s[92:93] offset:1792
	global_atomic_add v8, v1, s[92:93] offset:2048
	global_atomic_add v8, v1, s[92:93] offset:2304
	global_atomic_add v8, v1, s[92:93] offset:2560
	global_atomic_add v8, v1, s[92:93] offset:2816
	global_atomic_add v8, v1, s[92:93] offset:3072
	global_atomic_add v8, v1, s[92:93] offset:3328
	global_atomic_add v8, v1, s[92:93] offset:3584
	global_atomic_add v8, v1, s[92:93] offset:3840
	s_branch .Lxb5_done

.LBB0_908:
	s_cmp_gt_i32 s95, 7
	s_cselect_b64 s[4:5], -1, 0
	s_and_b64 s[0:1], s[0:1], s[4:5]
	s_andn2_b64 vcc, exec, s[0:1]
	s_cbranch_vccnz .LBB0_964
	s_waitcnt vmcnt(0)
	v_readlane_b32 s0, v245, 55
	v_readlane_b32 s1, v245, 56
	s_and_b64 vcc, exec, s[0:1]
	s_waitcnt lgkmcnt(0)
	s_barrier
	s_cbranch_vccnz .LBB0_963
	v_mbcnt_hi_u32_b32 v0, -1, v192
	v_cmp_eq_u32_e32 vcc, 0, v0
	s_and_saveexec_b64 s[0:1], vcc
	s_cbranch_execz .LBB0_962
	s_waitcnt vmcnt(0) lgkmcnt(0)
	v_mov_b32_e32 v1, 1
	v_readlane_b32 s11, v244, 43
	s_cmp_eq_u32 s11, 1
	s_cbranch_scc0 .Lxb6_glob
	s_and_b32 s12, s2, 7
	s_lshl_b32 s10, s12, 8
	s_add_i32 s10, s10, 0x6000
	v_mov_b32_e32 v6, s10
	global_atomic_add v6, v1, s[92:93]
	v_readlane_b32 s11, v244, 41
	s_sub_i32 s11, s11, s12
	s_add_i32 s11, s11, 7
	s_lshr_b32 s11, s11, 3
	s_mul_i32 s6, s11, 2
	s_branch .Lxb6_wait

.LBB0_981:
	s_cmp_gt_i32 s95, 8
	s_cselect_b64 s[4:5], -1, 0
	s_and_b64 s[0:1], s[0:1], s[4:5]
	s_andn2_b64 vcc, exec, s[0:1]
	s_cbranch_vccnz .LBB0_1037
	s_waitcnt vmcnt(0)
	v_readlane_b32 s0, v245, 55
	v_readlane_b32 s1, v245, 56
	s_and_b64 vcc, exec, s[0:1]
	s_waitcnt lgkmcnt(0)
	s_barrier
	s_cbranch_vccnz .LBB0_1036
	v_mbcnt_hi_u32_b32 v0, -1, v192
	v_cmp_eq_u32_e32 vcc, 0, v0
	s_and_saveexec_b64 s[0:1], vcc
	s_cbranch_execz .LBB0_1035
	s_waitcnt vmcnt(0) lgkmcnt(0)
	v_mov_b32_e32 v1, 1
	v_readlane_b32 s11, v244, 43
	s_cmp_eq_u32 s11, 1
	s_cbranch_scc0 .Lxb7_glob
	s_and_b32 s12, s2, 7
	s_lshl_b32 s10, s12, 8
	s_add_i32 s10, s10, 0x6000
	v_mov_b32_e32 v6, s10
	global_atomic_add v6, v1, s[92:93]
	v_readlane_b32 s11, v244, 41
	s_sub_i32 s11, s11, s12
	s_add_i32 s11, s11, 7
	s_lshr_b32 s11, s11, 3
	s_mul_i32 s6, s11, 3
	s_branch .Lxb7_wait
